# grid barrier leader: dropped the unused per-XCD release add and the waits for its own release atomics before the closing barrier
# speedup vs baseline: 1.0032x; 1.0032x over previous
.LBB0_168:
	s_or_b64 exec, exec, s[10:11]
	s_mov_b64 s[10:11], exec
	v_mbcnt_lo_u32_b32 v1, s10, 0
	v_mbcnt_hi_u32_b32 v1, s11, v1
	v_cmp_eq_u32_e32 vcc, 0, v1
	s_and_saveexec_b64 s[12:13], vcc
	s_cbranch_execz .LBB0_170
	s_bcnt1_i32_b64 s3, s[10:11]
	v_mov_b32_e32 v1, 0x2000
	v_mov_b32_e32 v2, s3
.LBB0_170:
	s_or_b64 exec, exec, s[12:13]
.LBB0_171:
	s_or_b64 exec, exec, s[0:1]
	v_readlane_b32 s4, v236, 4
	v_readlane_b32 s5, v236, 5
	s_waitcnt lgkmcnt(0)
	s_barrier

.LBB0_314:
	s_or_b64 exec, exec, s[8:9]
	s_mov_b64 s[8:9], exec
	v_mbcnt_lo_u32_b32 v1, s8, 0
	v_mbcnt_hi_u32_b32 v1, s9, v1
	v_cmp_eq_u32_e32 vcc, 0, v1
	s_and_saveexec_b64 s[10:11], vcc
	s_cbranch_execz .LBB0_316
	s_bcnt1_i32_b64 s3, s[8:9]
	v_mov_b32_e32 v1, 0x2000
	v_mov_b32_e32 v2, s3
.LBB0_316:
	s_or_b64 exec, exec, s[10:11]
.LBB0_317:
	s_or_b64 exec, exec, s[0:1]
	s_waitcnt lgkmcnt(0)
	s_barrier

.LBB0_507:
	s_or_b64 exec, exec, s[12:13]
	s_mov_b64 s[12:13], exec
	v_mbcnt_lo_u32_b32 v1, s12, 0
	v_mbcnt_hi_u32_b32 v1, s13, v1
	v_cmp_eq_u32_e32 vcc, 0, v1
	s_and_saveexec_b64 s[14:15], vcc
	s_cbranch_execz .LBB0_509
	s_bcnt1_i32_b64 s3, s[12:13]
	v_mov_b32_e32 v1, 0x2000
	v_mov_b32_e32 v2, s3
.LBB0_509:
	s_or_b64 exec, exec, s[14:15]
.LBB0_510:
	s_or_b64 exec, exec, s[0:1]
	v_readlane_b32 s4, v236, 4
	s_mov_b64 s[0:1], 0
	v_readlane_b32 s5, v236, 5
	s_waitcnt lgkmcnt(0)
	s_barrier

.LBB0_650:
	s_or_b64 exec, exec, s[14:15]
.LBB0_651:
	s_or_b64 exec, exec, s[8:9]
	s_mov_b64 s[8:9], 0
	s_waitcnt lgkmcnt(0)
	s_barrier

.LBB0_771:
	s_or_b64 exec, exec, s[12:13]
.LBB0_772:
	s_or_b64 exec, exec, s[6:7]
	s_mov_b64 s[6:7], 0
	s_waitcnt lgkmcnt(0)
	s_barrier

.LBB0_912:
	s_or_b64 exec, exec, s[12:13]
.LBB0_913:
	s_or_b64 exec, exec, s[0:1]
	s_mov_b64 s[0:1], 0
	v_readlane_b32 s4, v236, 4
	s_waitcnt lgkmcnt(0)
	s_barrier
	v_readlane_b32 s5, v236, 5

.LBB0_1247:
	s_or_b64 exec, exec, s[12:13]
.LBB0_1248:
	s_or_b64 exec, exec, s[0:1]
	s_mov_b64 s[0:1], 0
	v_readlane_b32 s4, v236, 4
	s_waitcnt lgkmcnt(0)
	s_barrier
	v_readlane_b32 s5, v236, 5

.LBB0_1416:
	s_or_b64 exec, exec, s[12:13]
.LBB0_1417:
	s_or_b64 exec, exec, s[6:7]
	v_readlane_b32 s4, v236, 4
	s_waitcnt lgkmcnt(0)
	s_barrier
	v_readlane_b32 s5, v236, 5

.LBB0_1643:
	s_or_b64 exec, exec, s[10:11]
	s_mov_b64 s[10:11], exec
	v_mbcnt_lo_u32_b32 v0, s10, 0
	v_mbcnt_hi_u32_b32 v0, s11, v0
	v_cmp_eq_u32_e32 vcc, 0, v0
	s_and_saveexec_b64 s[12:13], vcc
	s_cbranch_execz .LBB0_1645
	s_bcnt1_i32_b64 s3, s[10:11]
	v_mov_b32_e32 v0, 0x2000
	v_mov_b32_e32 v1, s3
.LBB0_1645:
	s_or_b64 exec, exec, s[12:13]
.LBB0_1646:
	s_or_b64 exec, exec, s[0:1]
	v_readlane_b32 s4, v236, 4
	v_readlane_b32 s5, v236, 5
	s_waitcnt lgkmcnt(0)
	s_barrier

.LBB0_1753:
	s_or_b64 exec, exec, s[12:13]
	s_mov_b64 s[12:13], exec
	v_mbcnt_lo_u32_b32 v0, s12, 0
	v_mbcnt_hi_u32_b32 v0, s13, v0
	v_cmp_eq_u32_e32 vcc, 0, v0
	s_and_saveexec_b64 s[14:15], vcc
	s_cbranch_execz .LBB0_1755
	s_bcnt1_i32_b64 s3, s[12:13]
	v_mov_b32_e32 v0, 0x2000
	v_mov_b32_e32 v1, s3
.LBB0_1755:
	s_or_b64 exec, exec, s[14:15]
.LBB0_1756:
	s_or_b64 exec, exec, s[8:9]
	s_mov_b64 s[8:9], 0
	s_waitcnt lgkmcnt(0)
	s_barrier

.LBB0_1880:
	s_or_b64 exec, exec, s[12:13]
.LBB0_1881:
	s_or_b64 exec, exec, s[6:7]
	s_mov_b64 s[6:7], 0
	s_waitcnt lgkmcnt(0)
	s_barrier

.LBB0_1994:
	s_or_b64 exec, exec, s[16:17]
	s_mov_b64 s[16:17], exec
	v_mbcnt_lo_u32_b32 v0, s16, 0
	v_mbcnt_hi_u32_b32 v0, s17, v0
	v_cmp_eq_u32_e32 vcc, 0, v0
	s_and_saveexec_b64 s[20:21], vcc
	s_cbranch_execz .LBB0_1996
	s_bcnt1_i32_b64 s3, s[16:17]
	v_mov_b32_e32 v0, 0x2000
	v_mov_b32_e32 v1, s3
.LBB0_1996:
	s_or_b64 exec, exec, s[20:21]
.LBB0_1997:
	s_or_b64 exec, exec, s[4:5]
	s_waitcnt lgkmcnt(0)
	v_mov_b32_e32 v0, v182
	s_barrier
	s_nop 0
	v_readfirstlane_b32 s3, v0
	s_cmp_gt_u32 s3, 63
	s_cselect_b64 s[4:5], -1, 0
	s_cmp_gt_i32 s2, 63
	s_cselect_b64 s[6:7], -1, 0
	s_or_b64 s[4:5], s[4:5], s[6:7]
	s_and_b64 vcc, exec, s[4:5]
	s_cbranch_vccnz .LBB0_2002
	v_and_b32_e32 v4, 63, v0
	v_lshlrev_b32_e32 v0, 4, v4
	v_mov_b32_e32 v1, 0
	v_lshl_add_u64 v[6:7], s[70:71], 0, v[0:1]
	s_mov_b64 s[6:7], 0x800
	s_lshl_b32 s3, s2, 8
	v_lshl_add_u64 v[6:7], v[6:7], 0, s[6:7]
	s_movk_i32 s6, 0xf800
	s_movk_i32 s16, 0xf000
	v_lshl_add_u64 v[2:3], s[68:69], 0, v[0:1]
	s_or_b32 s4, s3, 0xff
	s_lshl_b32 s3, s92, 8
	v_lshlrev_b32_e32 v4, 3, v4
	v_mov_b32_e32 v0, 0x358637bd
	s_mov_b32 s20, 0x800000
	s_mov_b32 s21, 0x3800000
	s_mov_b32 s7, -1
	s_mov_b32 s17, -1
